# final row normalisation (phase 15) rewritten: two rows in flight per wave (next row's loads issued before the current row is reduced and stored), wave sum by DPP + v_permlane swaps
# speedup vs baseline: 1.0021x; 1.0021x over previous
; #define RUN(n, ...) if (PH_ON(n)) { __VA_ARGS__ if (PROBE_PH == (n)) { __syncthreads(); __VA_ARGS__ } PH_END(n); }
; template <bool BF> __device__ __forceinline__ void rownorm(const float* src, const float* __restrict__ g, void* dst) {
;     const int lane = threadIdx.x & 63, wid = threadIdx.x >> 6;
;     for (int row = blockIdx.x * 8 + wid; row < NTOK; row += gridDim.x * 8) {
;         const float* s = src + (size_t)row * DM + lane * 4; f32x4 v[8]; float ss = 0.f;
; #pragma unroll
;         for (int i = 0; i < 8; ++i) { v[i] = *(const f32x4*)(s + i * 256); ss += v[i][0] * v[i][0] + v[i][1] * v[i][1] + v[i][2] * v[i][2] + v[i][3] * v[i][3]; }
; __global__ void __launch_bounds__(NTHREADS, 2) mega(Params p) {
;     ...
;     RUN(15, rownorm<false>(p.out, p.final_g, p.out);)
.LBB0_1299:
	s_cmp_lt_i32 s58, 16
	s_cselect_b64 s[0:1], -1, 0
	s_cmp_gt_i32 s59, 15
	s_cselect_b64 s[4:5], -1, 0
	s_and_b64 s[0:1], s[0:1], s[4:5]
	s_andn2_b64 vcc, exec, s[0:1]
	s_cbranch_vccnz .LBB0_1357
	s_mov_b64 exec, -1
	v_readfirstlane_b32 s0, v254
	s_nop 3
	s_lshr_b32 s1, s0, 6
	s_lshl_b32 s72, s2, 3
	s_add_u32 s72, s72, s1
	s_lshl_b32 s73, s96, 3
	s_mov_b64 s[2:3], exec
	s_mov_b32 s64, s54
	s_and_b32 s65, s55, 0xffff
	s_brev_b32 s66, -2
	s_mov_b32 s67, 0x27000
	v_and_b32_e32 v100, 63, v254
	v_lshlrev_b32_e32 v100, 4, v100
	v_add_u32_e32 v101, 0x1000, v100
	global_load_dwordx4 v[0:3], v100, s[52:53] offset:0
	global_load_dwordx4 v[4:7], v100, s[52:53] offset:1024
	global_load_dwordx4 v[8:11], v100, s[52:53] offset:2048
	global_load_dwordx4 v[12:15], v100, s[52:53] offset:3072
	global_load_dwordx4 v[16:19], v101, s[52:53] offset:0
	global_load_dwordx4 v[20:23], v101, s[52:53] offset:1024
	global_load_dwordx4 v[24:27], v101, s[52:53] offset:2048
	global_load_dwordx4 v[28:31], v101, s[52:53] offset:3072
	s_cmp_lt_u32 s72, 0x8000
	s_cbranch_scc0 .Lmy_ph15_end
	s_lshl_b32 s74, s72, 13
	s_add_u32 s72, s72, s73
	buffer_load_dwordx4 v[32:35], v100, s[64:67], s74 offen offset:0
	buffer_load_dwordx4 v[36:39], v100, s[64:67], s74 offen offset:1024
	buffer_load_dwordx4 v[40:43], v100, s[64:67], s74 offen offset:2048
	buffer_load_dwordx4 v[44:47], v100, s[64:67], s74 offen offset:3072
	buffer_load_dwordx4 v[48:51], v101, s[64:67], s74 offen offset:0
	buffer_load_dwordx4 v[52:55], v101, s[64:67], s74 offen offset:1024
	buffer_load_dwordx4 v[56:59], v101, s[64:67], s74 offen offset:2048
	buffer_load_dwordx4 v[60:63], v101, s[64:67], s74 offen offset:3072
	s_cmp_lt_u32 s72, 0x8000
	s_cselect_b32 s76, 1, 0
	s_cbranch_scc0 .Lmy_ph15_s0_nol
	s_lshl_b32 s75, s72, 13
	s_add_u32 s72, s72, s73
	buffer_load_dwordx4 v[64:67], v100, s[64:67], s75 offen offset:0
	buffer_load_dwordx4 v[68:71], v100, s[64:67], s75 offen offset:1024
	buffer_load_dwordx4 v[72:75], v100, s[64:67], s75 offen offset:2048
	buffer_load_dwordx4 v[76:79], v100, s[64:67], s75 offen offset:3072
	buffer_load_dwordx4 v[80:83], v101, s[64:67], s75 offen offset:0
	buffer_load_dwordx4 v[84:87], v101, s[64:67], s75 offen offset:1024
	buffer_load_dwordx4 v[88:91], v101, s[64:67], s75 offen offset:2048
	buffer_load_dwordx4 v[92:95], v101, s[64:67], s75 offen offset:3072
	s_waitcnt vmcnt(8)
	s_branch .Lmy_ph15_s0_go

; __device__ __forceinline__ unsigned cvt_pk_bf16(float lo, float hi) { unsigned r; asm volatile("v_cvt_pk_bf16_f32 %0, %1, %2" : "=v"(r) : "v"(lo), "v"(hi)); return r; }
; template <bool BF> __device__ __forceinline__ void rownorm(const float* src, const float* __restrict__ g, void* dst) {
;     ...
;         const float* s = src + (size_t)row * DM + lane * 4; f32x4 v[8]; float ss = 0.f;
; #pragma unroll
;         for (int i = 0; i < 8; ++i) { v[i] = *(const f32x4*)(s + i * 256); ss += v[i][0] * v[i][0] + v[i][1] * v[i][1] + v[i][2] * v[i][2] + v[i][3] * v[i][3]; }
; #pragma unroll
;         for (int o = 32; o >= 1; o >>= 1) ss += __shfl_xor(ss, o);
;         const float sc = rsqrtf(ss * (1.0f / DM) + 1e-6f);
; #pragma unroll
;         for (int i = 0; i < 8; ++i) { const f32x4 gv = *(const f32x4*)(g + lane * 4 + i * 256); const f32x4 o = v[i] * sc * gv;
;             if (BF) { u32x2 w; w.x = cvt_pk_bf16(o[0], o[1]); w.y = cvt_pk_bf16(o[2], o[3]); *(u32x2*)((u16*)dst + (size_t)row * DM + lane * 4 + i * 256) = w; }
;             else *(f32x4*)((float*)dst + (size_t)row * DM + lane * 4 + i * 256) = o; }
.Lmy_ph15_s0_go:
	v_pk_mul_f32 v[96:97], v[32:33], v[32:33]
	v_pk_fma_f32 v[96:97], v[34:35], v[34:35], v[96:97]
	v_pk_fma_f32 v[96:97], v[36:37], v[36:37], v[96:97]
	v_pk_fma_f32 v[96:97], v[38:39], v[38:39], v[96:97]
	v_pk_fma_f32 v[96:97], v[40:41], v[40:41], v[96:97]
	v_pk_fma_f32 v[96:97], v[42:43], v[42:43], v[96:97]
	v_pk_fma_f32 v[96:97], v[44:45], v[44:45], v[96:97]
	v_pk_fma_f32 v[96:97], v[46:47], v[46:47], v[96:97]
	v_pk_fma_f32 v[96:97], v[48:49], v[48:49], v[96:97]
	v_pk_fma_f32 v[96:97], v[50:51], v[50:51], v[96:97]
	v_pk_fma_f32 v[96:97], v[52:53], v[52:53], v[96:97]
	v_pk_fma_f32 v[96:97], v[54:55], v[54:55], v[96:97]
	v_pk_fma_f32 v[96:97], v[56:57], v[56:57], v[96:97]
	v_pk_fma_f32 v[96:97], v[58:59], v[58:59], v[96:97]
	v_pk_fma_f32 v[96:97], v[60:61], v[60:61], v[96:97]
	v_pk_fma_f32 v[96:97], v[62:63], v[62:63], v[96:97]
	v_add_f32_e32 v96, v96, v97
	s_nop 1
	v_add_f32_dpp v96, v96, v96 quad_perm:[1,0,3,2] row_mask:0xf bank_mask:0xf
	s_nop 1
	v_add_f32_dpp v96, v96, v96 quad_perm:[2,3,0,1] row_mask:0xf bank_mask:0xf
	s_nop 1
	v_add_f32_dpp v96, v96, v96 row_ror:4 row_mask:0xf bank_mask:0xf
	s_nop 1
	v_add_f32_dpp v96, v96, v96 row_ror:8 row_mask:0xf bank_mask:0xf
	v_mov_b32_e32 v98, v96
	s_nop 1
	v_permlane16_swap_b32 v98, v96
	v_add_f32_e32 v96, v96, v98
	v_mov_b32_e32 v98, v96
	s_nop 1
	v_permlane32_swap_b32 v98, v96
	v_add_f32_e32 v96, v96, v98
	v_mul_f32_e32 v96, 0x3a000000, v96
	v_add_f32_e32 v96, 0x358637bd, v96
	v_rsq_f32_e32 v96, v96
	s_nop 0
	v_pk_mul_f32 v[32:33], v[32:33], v[96:97] op_sel_hi:[1,0]
	v_pk_mul_f32 v[34:35], v[34:35], v[96:97] op_sel_hi:[1,0]
	v_pk_mul_f32 v[36:37], v[36:37], v[96:97] op_sel_hi:[1,0]
	v_pk_mul_f32 v[38:39], v[38:39], v[96:97] op_sel_hi:[1,0]
	v_pk_mul_f32 v[40:41], v[40:41], v[96:97] op_sel_hi:[1,0]
	v_pk_mul_f32 v[42:43], v[42:43], v[96:97] op_sel_hi:[1,0]
	v_pk_mul_f32 v[44:45], v[44:45], v[96:97] op_sel_hi:[1,0]
	v_pk_mul_f32 v[46:47], v[46:47], v[96:97] op_sel_hi:[1,0]
	v_pk_mul_f32 v[48:49], v[48:49], v[96:97] op_sel_hi:[1,0]
	v_pk_mul_f32 v[50:51], v[50:51], v[96:97] op_sel_hi:[1,0]
	v_pk_mul_f32 v[52:53], v[52:53], v[96:97] op_sel_hi:[1,0]
	v_pk_mul_f32 v[54:55], v[54:55], v[96:97] op_sel_hi:[1,0]
	v_pk_mul_f32 v[56:57], v[56:57], v[96:97] op_sel_hi:[1,0]
	v_pk_mul_f32 v[58:59], v[58:59], v[96:97] op_sel_hi:[1,0]
	v_pk_mul_f32 v[60:61], v[60:61], v[96:97] op_sel_hi:[1,0]
	v_pk_mul_f32 v[62:63], v[62:63], v[96:97] op_sel_hi:[1,0]
	v_pk_mul_f32 v[32:33], v[0:1], v[32:33]
	v_pk_mul_f32 v[34:35], v[2:3], v[34:35]
	v_pk_mul_f32 v[36:37], v[4:5], v[36:37]
	v_pk_mul_f32 v[38:39], v[6:7], v[38:39]
	v_pk_mul_f32 v[40:41], v[8:9], v[40:41]
	v_pk_mul_f32 v[42:43], v[10:11], v[42:43]
	v_pk_mul_f32 v[44:45], v[12:13], v[44:45]
	v_pk_mul_f32 v[46:47], v[14:15], v[46:47]
	v_pk_mul_f32 v[48:49], v[16:17], v[48:49]
	v_pk_mul_f32 v[50:51], v[18:19], v[50:51]
	v_pk_mul_f32 v[52:53], v[20:21], v[52:53]
	v_pk_mul_f32 v[54:55], v[22:23], v[54:55]
	v_pk_mul_f32 v[56:57], v[24:25], v[56:57]
	v_pk_mul_f32 v[58:59], v[26:27], v[58:59]
	v_pk_mul_f32 v[60:61], v[28:29], v[60:61]
	v_pk_mul_f32 v[62:63], v[30:31], v[62:63]
	buffer_store_dwordx4 v[32:35], v100, s[64:67], s74 offen offset:0
	buffer_store_dwordx4 v[36:39], v100, s[64:67], s74 offen offset:1024
	buffer_store_dwordx4 v[40:43], v100, s[64:67], s74 offen offset:2048
	buffer_store_dwordx4 v[44:47], v100, s[64:67], s74 offen offset:3072
	buffer_store_dwordx4 v[48:51], v101, s[64:67], s74 offen offset:0
	buffer_store_dwordx4 v[52:55], v101, s[64:67], s74 offen offset:1024
	buffer_store_dwordx4 v[56:59], v101, s[64:67], s74 offen offset:2048
	buffer_store_dwordx4 v[60:63], v101, s[64:67], s74 offen offset:3072
	s_cmp_eq_u32 s76, 1
	s_cbranch_scc0 .Lmy_ph15_end
.Lmy_ph15_loop:
	s_cmp_lt_u32 s72, 0x8000
	s_cselect_b32 s76, 1, 0
	s_cbranch_scc0 .Lmy_ph15_s1_nol
	s_lshl_b32 s74, s72, 13
	s_add_u32 s72, s72, s73
	buffer_load_dwordx4 v[32:35], v100, s[64:67], s74 offen offset:0
	buffer_load_dwordx4 v[36:39], v100, s[64:67], s74 offen offset:1024
	buffer_load_dwordx4 v[40:43], v100, s[64:67], s74 offen offset:2048
	buffer_load_dwordx4 v[44:47], v100, s[64:67], s74 offen offset:3072
	buffer_load_dwordx4 v[48:51], v101, s[64:67], s74 offen offset:0
	buffer_load_dwordx4 v[52:55], v101, s[64:67], s74 offen offset:1024
	buffer_load_dwordx4 v[56:59], v101, s[64:67], s74 offen offset:2048
	buffer_load_dwordx4 v[60:63], v101, s[64:67], s74 offen offset:3072
	s_waitcnt vmcnt(16)
	s_branch .Lmy_ph15_s1_go
; __device__ __forceinline__ unsigned cvt_pk_bf16(float lo, float hi) { unsigned r; asm volatile("v_cvt_pk_bf16_f32 %0, %1, %2" : "=v"(r) : "v"(lo), "v"(hi)); return r; }
; template <bool BF> __device__ __forceinline__ void rownorm(const float* src, const float* __restrict__ g, void* dst) {
;     ...
;     for (int row = blockIdx.x * 8 + wid; row < NTOK; row += gridDim.x * 8) {
;         const float* s = src + (size_t)row * DM + lane * 4; f32x4 v[8]; float ss = 0.f;
; #pragma unroll
;         for (int i = 0; i < 8; ++i) { v[i] = *(const f32x4*)(s + i * 256); ss += v[i][0] * v[i][0] + v[i][1] * v[i][1] + v[i][2] * v[i][2] + v[i][3] * v[i][3]; }
; #pragma unroll
;         for (int o = 32; o >= 1; o >>= 1) ss += __shfl_xor(ss, o);
;         const float sc = rsqrtf(ss * (1.0f / DM) + 1e-6f);
; #pragma unroll
;         for (int i = 0; i < 8; ++i) { const f32x4 gv = *(const f32x4*)(g + lane * 4 + i * 256); const f32x4 o = v[i] * sc * gv;
;             if (BF) { u32x2 w; w.x = cvt_pk_bf16(o[0], o[1]); w.y = cvt_pk_bf16(o[2], o[3]); *(u32x2*)((u16*)dst + (size_t)row * DM + lane * 4 + i * 256) = w; }
;             else *(f32x4*)((float*)dst + (size_t)row * DM + lane * 4 + i * 256) = o; }
.Lmy_ph15_s1_nol:
	s_waitcnt vmcnt(8)
.Lmy_ph15_s1_go:
	v_pk_mul_f32 v[96:97], v[64:65], v[64:65]
	v_pk_fma_f32 v[96:97], v[66:67], v[66:67], v[96:97]
	v_pk_fma_f32 v[96:97], v[68:69], v[68:69], v[96:97]
	v_pk_fma_f32 v[96:97], v[70:71], v[70:71], v[96:97]
	v_pk_fma_f32 v[96:97], v[72:73], v[72:73], v[96:97]
	v_pk_fma_f32 v[96:97], v[74:75], v[74:75], v[96:97]
	v_pk_fma_f32 v[96:97], v[76:77], v[76:77], v[96:97]
	v_pk_fma_f32 v[96:97], v[78:79], v[78:79], v[96:97]
	v_pk_fma_f32 v[96:97], v[80:81], v[80:81], v[96:97]
	v_pk_fma_f32 v[96:97], v[82:83], v[82:83], v[96:97]
	v_pk_fma_f32 v[96:97], v[84:85], v[84:85], v[96:97]
	v_pk_fma_f32 v[96:97], v[86:87], v[86:87], v[96:97]
	v_pk_fma_f32 v[96:97], v[88:89], v[88:89], v[96:97]
	v_pk_fma_f32 v[96:97], v[90:91], v[90:91], v[96:97]
	v_pk_fma_f32 v[96:97], v[92:93], v[92:93], v[96:97]
	v_pk_fma_f32 v[96:97], v[94:95], v[94:95], v[96:97]
	v_add_f32_e32 v96, v96, v97
	s_nop 1
	v_add_f32_dpp v96, v96, v96 quad_perm:[1,0,3,2] row_mask:0xf bank_mask:0xf
	s_nop 1
	v_add_f32_dpp v96, v96, v96 quad_perm:[2,3,0,1] row_mask:0xf bank_mask:0xf
	s_nop 1
	v_add_f32_dpp v96, v96, v96 row_ror:4 row_mask:0xf bank_mask:0xf
	s_nop 1
	v_add_f32_dpp v96, v96, v96 row_ror:8 row_mask:0xf bank_mask:0xf
	v_mov_b32_e32 v98, v96
	s_nop 1
	v_permlane16_swap_b32 v98, v96
	v_add_f32_e32 v96, v96, v98
	v_mov_b32_e32 v98, v96
	s_nop 1
	v_permlane32_swap_b32 v98, v96
	v_add_f32_e32 v96, v96, v98
	v_mul_f32_e32 v96, 0x3a000000, v96
	v_add_f32_e32 v96, 0x358637bd, v96
	v_rsq_f32_e32 v96, v96
	s_nop 0
	v_pk_mul_f32 v[64:65], v[64:65], v[96:97] op_sel_hi:[1,0]
	v_pk_mul_f32 v[66:67], v[66:67], v[96:97] op_sel_hi:[1,0]
	v_pk_mul_f32 v[68:69], v[68:69], v[96:97] op_sel_hi:[1,0]
	v_pk_mul_f32 v[70:71], v[70:71], v[96:97] op_sel_hi:[1,0]
	v_pk_mul_f32 v[72:73], v[72:73], v[96:97] op_sel_hi:[1,0]
	v_pk_mul_f32 v[74:75], v[74:75], v[96:97] op_sel_hi:[1,0]
	v_pk_mul_f32 v[76:77], v[76:77], v[96:97] op_sel_hi:[1,0]
	v_pk_mul_f32 v[78:79], v[78:79], v[96:97] op_sel_hi:[1,0]
	v_pk_mul_f32 v[80:81], v[80:81], v[96:97] op_sel_hi:[1,0]
	v_pk_mul_f32 v[82:83], v[82:83], v[96:97] op_sel_hi:[1,0]
	v_pk_mul_f32 v[84:85], v[84:85], v[96:97] op_sel_hi:[1,0]
	v_pk_mul_f32 v[86:87], v[86:87], v[96:97] op_sel_hi:[1,0]
	v_pk_mul_f32 v[88:89], v[88:89], v[96:97] op_sel_hi:[1,0]
	v_pk_mul_f32 v[90:91], v[90:91], v[96:97] op_sel_hi:[1,0]
	v_pk_mul_f32 v[92:93], v[92:93], v[96:97] op_sel_hi:[1,0]
	v_pk_mul_f32 v[94:95], v[94:95], v[96:97] op_sel_hi:[1,0]
	v_pk_mul_f32 v[64:65], v[0:1], v[64:65]
	v_pk_mul_f32 v[66:67], v[2:3], v[66:67]
	v_pk_mul_f32 v[68:69], v[4:5], v[68:69]
	v_pk_mul_f32 v[70:71], v[6:7], v[70:71]
	v_pk_mul_f32 v[72:73], v[8:9], v[72:73]
	v_pk_mul_f32 v[74:75], v[10:11], v[74:75]
	v_pk_mul_f32 v[76:77], v[12:13], v[76:77]
	v_pk_mul_f32 v[78:79], v[14:15], v[78:79]
	v_pk_mul_f32 v[80:81], v[16:17], v[80:81]
	v_pk_mul_f32 v[82:83], v[18:19], v[82:83]
	v_pk_mul_f32 v[84:85], v[20:21], v[84:85]
	v_pk_mul_f32 v[86:87], v[22:23], v[86:87]
	v_pk_mul_f32 v[88:89], v[24:25], v[88:89]
	v_pk_mul_f32 v[90:91], v[26:27], v[90:91]
	v_pk_mul_f32 v[92:93], v[28:29], v[92:93]
	v_pk_mul_f32 v[94:95], v[30:31], v[94:95]
	buffer_store_dwordx4 v[64:67], v100, s[64:67], s75 offen offset:0
	buffer_store_dwordx4 v[68:71], v100, s[64:67], s75 offen offset:1024
	buffer_store_dwordx4 v[72:75], v100, s[64:67], s75 offen offset:2048
	buffer_store_dwordx4 v[76:79], v100, s[64:67], s75 offen offset:3072
	buffer_store_dwordx4 v[80:83], v101, s[64:67], s75 offen offset:0
	buffer_store_dwordx4 v[84:87], v101, s[64:67], s75 offen offset:1024
	buffer_store_dwordx4 v[88:91], v101, s[64:67], s75 offen offset:2048
	buffer_store_dwordx4 v[92:95], v101, s[64:67], s75 offen offset:3072
	s_cmp_eq_u32 s76, 1
	s_cbranch_scc0 .Lmy_ph15_end
	s_cmp_lt_u32 s72, 0x8000
	s_cselect_b32 s76, 1, 0
	s_cbranch_scc0 .Lmy_ph15_s2_nol
	s_lshl_b32 s75, s72, 13
	s_add_u32 s72, s72, s73
	buffer_load_dwordx4 v[64:67], v100, s[64:67], s75 offen offset:0
	buffer_load_dwordx4 v[68:71], v100, s[64:67], s75 offen offset:1024
	buffer_load_dwordx4 v[72:75], v100, s[64:67], s75 offen offset:2048
	buffer_load_dwordx4 v[76:79], v100, s[64:67], s75 offen offset:3072
	buffer_load_dwordx4 v[80:83], v101, s[64:67], s75 offen offset:0
	buffer_load_dwordx4 v[84:87], v101, s[64:67], s75 offen offset:1024
	buffer_load_dwordx4 v[88:91], v101, s[64:67], s75 offen offset:2048
	buffer_load_dwordx4 v[92:95], v101, s[64:67], s75 offen offset:3072
	s_waitcnt vmcnt(16)
	s_branch .Lmy_ph15_s2_go

; __device__ __forceinline__ unsigned cvt_pk_bf16(float lo, float hi) { unsigned r; asm volatile("v_cvt_pk_bf16_f32 %0, %1, %2" : "=v"(r) : "v"(lo), "v"(hi)); return r; }
; __device__ __forceinline__ unsigned xb_add(unsigned* p, unsigned v) { return __hip_atomic_fetch_add(p, v, __ATOMIC_RELAXED, __HIP_MEMORY_SCOPE_AGENT); }
; template <bool BF> __device__ __forceinline__ void rownorm(const float* src, const float* __restrict__ g, void* dst) {
;     ...
;     for (int row = blockIdx.x * 8 + wid; row < NTOK; row += gridDim.x * 8) {
;         const float* s = src + (size_t)row * DM + lane * 4; f32x4 v[8]; float ss = 0.f;
; #pragma unroll
;         for (int i = 0; i < 8; ++i) { v[i] = *(const f32x4*)(s + i * 256); ss += v[i][0] * v[i][0] + v[i][1] * v[i][1] + v[i][2] * v[i][2] + v[i][3] * v[i][3]; }
; #pragma unroll
;         for (int o = 32; o >= 1; o >>= 1) ss += __shfl_xor(ss, o);
;         const float sc = rsqrtf(ss * (1.0f / DM) + 1e-6f);
; #pragma unroll
;         for (int i = 0; i < 8; ++i) { const f32x4 gv = *(const f32x4*)(g + lane * 4 + i * 256); const f32x4 o = v[i] * sc * gv;
;             if (BF) { u32x2 w; w.x = cvt_pk_bf16(o[0], o[1]); w.y = cvt_pk_bf16(o[2], o[3]); *(u32x2*)((u16*)dst + (size_t)row * DM + lane * 4 + i * 256) = w; }
;             else *(f32x4*)((float*)dst + (size_t)row * DM + lane * 4 + i * 256) = o; }
; __device__ __forceinline__ void xcd_barrier(const XcdBarrier& b) {
;     asm volatile("s_waitcnt vmcnt(0)" ::: "memory");
;     __syncthreads();
;     if (threadIdx.x == 0) {
;         unsigned* bar = b.bar;
;         __builtin_amdgcn_s_waitcnt(0);
;         unsigned nloc = b.st[0], nx = b.st[1];
;         if (nloc == 0u) { xcd_barrier_complete(bar, b.x, nloc, nx); b.st[0] = nloc; b.st[1] = nx; }
;         const unsigned old = xb_add(&bar[XB_XSUB(b.x)], 1u);
.Lmy_ph15_s2_go:
	v_pk_mul_f32 v[96:97], v[32:33], v[32:33]
	v_pk_fma_f32 v[96:97], v[34:35], v[34:35], v[96:97]
	v_pk_fma_f32 v[96:97], v[36:37], v[36:37], v[96:97]
	v_pk_fma_f32 v[96:97], v[38:39], v[38:39], v[96:97]
	v_pk_fma_f32 v[96:97], v[40:41], v[40:41], v[96:97]
	v_pk_fma_f32 v[96:97], v[42:43], v[42:43], v[96:97]
	v_pk_fma_f32 v[96:97], v[44:45], v[44:45], v[96:97]
	v_pk_fma_f32 v[96:97], v[46:47], v[46:47], v[96:97]
	v_pk_fma_f32 v[96:97], v[48:49], v[48:49], v[96:97]
	v_pk_fma_f32 v[96:97], v[50:51], v[50:51], v[96:97]
	v_pk_fma_f32 v[96:97], v[52:53], v[52:53], v[96:97]
	v_pk_fma_f32 v[96:97], v[54:55], v[54:55], v[96:97]
	v_pk_fma_f32 v[96:97], v[56:57], v[56:57], v[96:97]
	v_pk_fma_f32 v[96:97], v[58:59], v[58:59], v[96:97]
	v_pk_fma_f32 v[96:97], v[60:61], v[60:61], v[96:97]
	v_pk_fma_f32 v[96:97], v[62:63], v[62:63], v[96:97]
	v_add_f32_e32 v96, v96, v97
	s_nop 1
	v_add_f32_dpp v96, v96, v96 quad_perm:[1,0,3,2] row_mask:0xf bank_mask:0xf
	s_nop 1
	v_add_f32_dpp v96, v96, v96 quad_perm:[2,3,0,1] row_mask:0xf bank_mask:0xf
	s_nop 1
	v_add_f32_dpp v96, v96, v96 row_ror:4 row_mask:0xf bank_mask:0xf
	s_nop 1
	v_add_f32_dpp v96, v96, v96 row_ror:8 row_mask:0xf bank_mask:0xf
	v_mov_b32_e32 v98, v96
	s_nop 1
	v_permlane16_swap_b32 v98, v96
	v_add_f32_e32 v96, v96, v98
	v_mov_b32_e32 v98, v96
	s_nop 1
	v_permlane32_swap_b32 v98, v96
	v_add_f32_e32 v96, v96, v98
	v_mul_f32_e32 v96, 0x3a000000, v96
	v_add_f32_e32 v96, 0x358637bd, v96
	v_rsq_f32_e32 v96, v96
	s_nop 0
	v_pk_mul_f32 v[32:33], v[32:33], v[96:97] op_sel_hi:[1,0]
	v_pk_mul_f32 v[34:35], v[34:35], v[96:97] op_sel_hi:[1,0]
	v_pk_mul_f32 v[36:37], v[36:37], v[96:97] op_sel_hi:[1,0]
	v_pk_mul_f32 v[38:39], v[38:39], v[96:97] op_sel_hi:[1,0]
	v_pk_mul_f32 v[40:41], v[40:41], v[96:97] op_sel_hi:[1,0]
	v_pk_mul_f32 v[42:43], v[42:43], v[96:97] op_sel_hi:[1,0]
	v_pk_mul_f32 v[44:45], v[44:45], v[96:97] op_sel_hi:[1,0]
	v_pk_mul_f32 v[46:47], v[46:47], v[96:97] op_sel_hi:[1,0]
	v_pk_mul_f32 v[48:49], v[48:49], v[96:97] op_sel_hi:[1,0]
	v_pk_mul_f32 v[50:51], v[50:51], v[96:97] op_sel_hi:[1,0]
	v_pk_mul_f32 v[52:53], v[52:53], v[96:97] op_sel_hi:[1,0]
	v_pk_mul_f32 v[54:55], v[54:55], v[96:97] op_sel_hi:[1,0]
	v_pk_mul_f32 v[56:57], v[56:57], v[96:97] op_sel_hi:[1,0]
	v_pk_mul_f32 v[58:59], v[58:59], v[96:97] op_sel_hi:[1,0]
	v_pk_mul_f32 v[60:61], v[60:61], v[96:97] op_sel_hi:[1,0]
	v_pk_mul_f32 v[62:63], v[62:63], v[96:97] op_sel_hi:[1,0]
	v_pk_mul_f32 v[32:33], v[0:1], v[32:33]
	v_pk_mul_f32 v[34:35], v[2:3], v[34:35]
	v_pk_mul_f32 v[36:37], v[4:5], v[36:37]
	v_pk_mul_f32 v[38:39], v[6:7], v[38:39]
	v_pk_mul_f32 v[40:41], v[8:9], v[40:41]
	v_pk_mul_f32 v[42:43], v[10:11], v[42:43]
	v_pk_mul_f32 v[44:45], v[12:13], v[44:45]
	v_pk_mul_f32 v[46:47], v[14:15], v[46:47]
	v_pk_mul_f32 v[48:49], v[16:17], v[48:49]
	v_pk_mul_f32 v[50:51], v[18:19], v[50:51]
	v_pk_mul_f32 v[52:53], v[20:21], v[52:53]
	v_pk_mul_f32 v[54:55], v[22:23], v[54:55]
	v_pk_mul_f32 v[56:57], v[24:25], v[56:57]
	v_pk_mul_f32 v[58:59], v[26:27], v[58:59]
	v_pk_mul_f32 v[60:61], v[28:29], v[60:61]
	v_pk_mul_f32 v[62:63], v[30:31], v[62:63]
	buffer_store_dwordx4 v[32:35], v100, s[64:67], s74 offen offset:0
	buffer_store_dwordx4 v[36:39], v100, s[64:67], s74 offen offset:1024
	buffer_store_dwordx4 v[40:43], v100, s[64:67], s74 offen offset:2048
	buffer_store_dwordx4 v[44:47], v100, s[64:67], s74 offen offset:3072
	buffer_store_dwordx4 v[48:51], v101, s[64:67], s74 offen offset:0
	buffer_store_dwordx4 v[52:55], v101, s[64:67], s74 offen offset:1024
	buffer_store_dwordx4 v[56:59], v101, s[64:67], s74 offen offset:2048
	buffer_store_dwordx4 v[60:63], v101, s[64:67], s74 offen offset:3072
	s_cmp_eq_u32 s76, 1
	s_cbranch_scc0 .Lmy_ph15_end
	s_branch .Lmy_ph15_loop
.Lmy_ph15_end:
.LBB0_1303:
	s_or_b64 exec, exec, s[2:3]
	s_cmp_lt_u32 s59, 17
	s_cbranch_scc1 .LBB0_1357
	s_waitcnt vmcnt(0)
	s_waitcnt lgkmcnt(0)
	s_barrier
	s_and_saveexec_b64 s[0:1], s[10:11]
	s_cbranch_execz .LBB0_1356
	s_add_i32 s2, 0, 0x20000
	s_waitcnt vmcnt(10)
	v_mov_b32_e32 v0, s2
	s_waitcnt vmcnt(0) expcnt(0) lgkmcnt(0)
	ds_read_b32 v2, v0
	s_add_i32 s2, 0, 0x20004
	v_mov_b32_e32 v0, s2
	ds_read_b32 v0, v0
	s_waitcnt lgkmcnt(1)
	v_cmp_ne_u32_e32 vcc, 0, v2
	s_cbranch_vccnz .LBB0_1320
	v_readlane_b32 s2, v255, 0
	s_mul_i32 s46, s97, s2
	s_add_u32 s2, s56, 0x3fa00200
	s_addc_u32 s3, s57, 0
	s_add_u32 s4, s56, 0x3fa00400
	s_addc_u32 s5, s57, 0
	s_add_u32 s6, s56, 0x3fa00500
	s_addc_u32 s7, s57, 0
	s_add_u32 s8, s56, 0x3fa00600
	s_addc_u32 s9, s57, 0
	s_add_u32 s10, s56, 0x3fa00700
	s_addc_u32 s11, s57, 0
	s_add_u32 s12, s56, 0x3fa00800
	s_addc_u32 s13, s57, 0
	s_add_u32 s14, s56, 0x3fa00900
	s_addc_u32 s15, s57, 0
	s_add_u32 s16, s56, 0x3fa00a00
	s_addc_u32 s17, s57, 0
	s_add_u32 s18, s56, 0x3fa00b00
	s_addc_u32 s19, s57, 0
	s_add_u32 s20, s56, 0x3fa00c00
	s_addc_u32 s21, s57, 0
	s_add_u32 s22, s56, 0x3fa00d00
	s_addc_u32 s23, s57, 0
	s_add_u32 s24, s56, 0x3fa00e00
	s_addc_u32 s25, s57, 0
	s_add_u32 s26, s56, 0x3fa00f00
	s_addc_u32 s27, s57, 0
	s_add_u32 s28, s56, 0x3fa01000
	s_addc_u32 s29, s57, 0
	s_add_u32 s30, s56, 0x3fa01100
	s_addc_u32 s31, s57, 0
	s_add_u32 s36, s56, 0x3fa01200
	s_addc_u32 s37, s57, 0
	s_add_u32 s38, s56, 0x3fa01300
	s_mul_i32 s46, s46, s96
	s_addc_u32 s39, s57, 0
	s_mov_b32 s47, 1
	v_mov_b32_e32 v16, 0
	s_branch .LBB0_1308
